# attention: loop-invariant cross-lane exchange address prep (4 VALU) moved behind the lane-local no-rescale branch so the fast path skips it; plus sticky SGPR flag for the zero-reference test
# baseline (speedup 1.0000x reference)
.LBB0_961:
	s_bitcmp1_b32 s35, 0
	s_cselect_b32 s35, 0xac00, 0
	s_add_i32 s35, s35, 0
	v_add3_u32 v1, s35, v209, v204
	ds_read_b128 v[2:5], v1
	ds_read_b128 v[6:9], v1 offset:32
	ds_read_b128 v[10:13], v1 offset:12800
	ds_read_b128 v[96:99], v1 offset:12832
	v_add_u32_e32 v14, s35, v210
	ds_read_b128 v[180:183], v1 offset:64
	ds_read_b128 v[216:219], v1 offset:96
	ds_read_b128 v[220:223], v1 offset:12864
	ds_read_b128 v[224:227], v1 offset:12896
	s_waitcnt lgkmcnt(5)
	v_mfma_f32_32x32x16_bf16 v[80:95], v[10:13], v[132:135], 0
	s_waitcnt lgkmcnt(4)
	v_mfma_f32_32x32x16_bf16 v[80:95], v[96:99], v[136:139], v[80:95]
	v_mfma_f32_32x32x16_bf16 v[96:111], v[2:5], v[132:135], 0
	ds_read_b128 v[2:5], v1 offset:128
	ds_read_b128 v[10:13], v1 offset:160
	ds_read_b128 v[228:231], v1 offset:12928
	ds_read_b128 v[232:235], v1 offset:12960
	v_mfma_f32_32x32x16_bf16 v[96:111], v[6:9], v[136:139], v[96:111]
	s_waitcnt lgkmcnt(7)
	v_mfma_f32_32x32x16_bf16 v[96:111], v[180:183], v[140:143], v[96:111]
	s_waitcnt lgkmcnt(5)
	v_mfma_f32_32x32x16_bf16 v[80:95], v[220:223], v[140:143], v[80:95]
	v_mfma_f32_32x32x16_bf16 v[96:111], v[216:219], v[144:147], v[96:111]
	ds_read_b128 v[6:9], v1 offset:192
	ds_read_b128 v[180:183], v1 offset:224
	ds_read_b128 v[216:219], v1 offset:12992
	ds_read_b128 v[220:223], v1 offset:13024
	s_waitcnt lgkmcnt(8)
	v_mfma_f32_32x32x16_bf16 v[80:95], v[224:227], v[144:147], v[80:95]
	s_waitcnt lgkmcnt(7)
	v_mfma_f32_32x32x16_bf16 v[96:111], v[2:5], v[148:151], v[96:111]
	s_waitcnt lgkmcnt(5)
	v_mfma_f32_32x32x16_bf16 v[80:95], v[228:231], v[148:151], v[80:95]
	v_mfma_f32_32x32x16_bf16 v[96:111], v[10:13], v[152:155], v[96:111]
	ds_read_b128 v[2:5], v1 offset:256
	ds_read_b128 v[10:13], v1 offset:288
	ds_read_b128 v[224:227], v1 offset:13056
	ds_read_b128 v[228:231], v1 offset:13088
	s_waitcnt lgkmcnt(8)
	v_mfma_f32_32x32x16_bf16 v[80:95], v[232:235], v[152:155], v[80:95]
	s_waitcnt lgkmcnt(7)
	v_mfma_f32_32x32x16_bf16 v[96:111], v[6:9], v[156:159], v[96:111]
	s_waitcnt lgkmcnt(5)
	v_mfma_f32_32x32x16_bf16 v[80:95], v[216:219], v[156:159], v[80:95]
	ds_read_b128 v[216:219], v1 offset:320
	ds_read_b128 v[232:235], v1 offset:352
	ds_read_b128 v[236:239], v1 offset:13120
	ds_read_b128 v[240:243], v1 offset:13152
	v_mfma_f32_32x32x16_bf16 v[96:111], v[180:183], v[160:163], v[96:111]
	s_waitcnt lgkmcnt(8)
	v_mfma_f32_32x32x16_bf16 v[80:95], v[220:223], v[160:163], v[80:95]
	v_add_u32_e32 v1, v14, v204
	s_waitcnt lgkmcnt(7)
	v_mfma_f32_32x32x16_bf16 v[96:111], v[2:5], v[164:167], v[96:111]
	s_waitcnt lgkmcnt(5)
	v_mfma_f32_32x32x16_bf16 v[80:95], v[224:227], v[164:167], v[80:95]
	v_mfma_f32_32x32x16_bf16 v[96:111], v[10:13], v[168:171], v[96:111]
	ds_read_b128 v[180:183], v1 offset:25600
	ds_read_b128 v[10:13], v1 offset:25632
	ds_read_b128 v[6:9], v1 offset:25664
	ds_read_b128 v[2:5], v1 offset:25696
	s_waitcnt lgkmcnt(8)
	v_mfma_f32_32x32x16_bf16 v[80:95], v[228:231], v[168:171], v[80:95]
	s_waitcnt lgkmcnt(7)
	v_mfma_f32_32x32x16_bf16 v[96:111], v[216:219], v[172:175], v[96:111]
	s_waitcnt lgkmcnt(5)
	v_mfma_f32_32x32x16_bf16 v[80:95], v[236:239], v[172:175], v[80:95]
	v_mfma_f32_32x32x16_bf16 v[96:111], v[232:235], v[176:179], v[96:111]
	s_waitcnt lgkmcnt(4)
	v_mfma_f32_32x32x16_bf16 v[80:95], v[240:243], v[176:179], v[80:95]
	s_nop 15
	s_nop 3
	s_nop 0
	v_max3_f32 v14, v96, v97, v98
	v_max3_f32 v215, v99, v100, v101
	v_max3_f32 v15, v80, v81, v82
	v_max3_f32 v216, v83, v84, v85
	v_max3_f32 v217, v102, v103, v104
	v_max3_f32 v218, v86, v87, v88
	v_max3_f32 v220, v89, v90, v91
	v_max3_f32 v219, v105, v106, v107
	v_max3_f32 v221, v108, v109, v110
	v_max3_f32 v222, v92, v93, v94
	s_nop 0
	v_max3_f32 v14, v14, v215, v217
	v_max3_f32 v215, v216, v218, v220
	v_max3_f32 v15, v219, v221, v15
	v_max3_f32 v216, v222, v111, v95
	s_nop 0
	v_max3_f32 v14, v14, v15, v215
	v_max3_f32 v14, v14, v216, v216
	v_sub_f32_e32 v216, v14, v214
	v_cmp_ge_f32_e64 s[98:99], s43, v216
	s_cmp_eq_u64 s[98:99], exec
	s_cbranch_scc1 .Lattn_nobp
	v_and_b32_e32 v215, 64, v212
	v_xor_b32_e32 v15, 32, v212
	v_add_u32_e32 v215, 64, v215
	v_cmp_lt_i32_e32 vcc, v15, v215
	s_nop 1
	v_cndmask_b32_e32 v15, v212, v15, vcc
	v_lshlrev_b32_e32 v15, 2, v15
	ds_bpermute_b32 v15, v15, v14
	v_max_f32_e32 v14, v14, v14
	s_waitcnt lgkmcnt(0)
	v_max_f32_e32 v15, v15, v15
	v_max_f32_e32 v14, v14, v15
	v_sub_f32_e32 v15, v14, v214
	v_cmp_ge_f32_e32 vcc, s43, v15
	s_cmp_eq_u64 vcc, exec
	s_cbranch_scc1 .LBB0_963
	v_max_f32_e32 v14, v14, v14
	v_max_f32_e32 v15, v214, v214
	v_max_f32_e32 v15, v15, v14
	v_sub_f32_e32 v14, v214, v15
	v_exp_f32_e32 v14, v14
	v_mov_b32_e32 v214, v15
	s_mov_b32 s100, 1
	v_pk_mul_f32 v[78:79], v[78:79], v[14:15] op_sel_hi:[1,0]
	v_pk_mul_f32 v[76:77], v[76:77], v[14:15] op_sel_hi:[1,0]
	v_pk_mul_f32 v[74:75], v[74:75], v[14:15] op_sel_hi:[1,0]
	v_pk_mul_f32 v[72:73], v[72:73], v[14:15] op_sel_hi:[1,0]
	v_pk_mul_f32 v[70:71], v[70:71], v[14:15] op_sel_hi:[1,0]
	v_pk_mul_f32 v[68:69], v[68:69], v[14:15] op_sel_hi:[1,0]
	v_pk_mul_f32 v[66:67], v[66:67], v[14:15] op_sel_hi:[1,0]
	v_pk_mul_f32 v[64:65], v[64:65], v[14:15] op_sel_hi:[1,0]
	v_pk_mul_f32 v[62:63], v[62:63], v[14:15] op_sel_hi:[1,0]
	v_pk_mul_f32 v[60:61], v[60:61], v[14:15] op_sel_hi:[1,0]
	v_pk_mul_f32 v[58:59], v[58:59], v[14:15] op_sel_hi:[1,0]
	v_pk_mul_f32 v[56:57], v[56:57], v[14:15] op_sel_hi:[1,0]
	v_pk_mul_f32 v[54:55], v[54:55], v[14:15] op_sel_hi:[1,0]
	v_pk_mul_f32 v[52:53], v[52:53], v[14:15] op_sel_hi:[1,0]
	v_pk_mul_f32 v[50:51], v[50:51], v[14:15] op_sel_hi:[1,0]
	v_pk_mul_f32 v[48:49], v[48:49], v[14:15] op_sel_hi:[1,0]
	v_pk_mul_f32 v[46:47], v[46:47], v[14:15] op_sel_hi:[1,0]
	v_pk_mul_f32 v[44:45], v[44:45], v[14:15] op_sel_hi:[1,0]
	v_pk_mul_f32 v[42:43], v[42:43], v[14:15] op_sel_hi:[1,0]
	v_pk_mul_f32 v[40:41], v[40:41], v[14:15] op_sel_hi:[1,0]
	v_pk_mul_f32 v[38:39], v[38:39], v[14:15] op_sel_hi:[1,0]
	v_pk_mul_f32 v[36:37], v[36:37], v[14:15] op_sel_hi:[1,0]
	v_pk_mul_f32 v[34:35], v[34:35], v[14:15] op_sel_hi:[1,0]
	v_pk_mul_f32 v[32:33], v[32:33], v[14:15] op_sel_hi:[1,0]
	v_pk_mul_f32 v[30:31], v[30:31], v[14:15] op_sel_hi:[1,0]
	v_pk_mul_f32 v[28:29], v[28:29], v[14:15] op_sel_hi:[1,0]
	v_pk_mul_f32 v[26:27], v[26:27], v[14:15] op_sel_hi:[1,0]
	v_pk_mul_f32 v[24:25], v[24:25], v[14:15] op_sel_hi:[1,0]
	v_pk_mul_f32 v[22:23], v[22:23], v[14:15] op_sel_hi:[1,0]
	v_pk_mul_f32 v[20:21], v[20:21], v[14:15] op_sel_hi:[1,0]
	v_pk_mul_f32 v[18:19], v[18:19], v[14:15] op_sel_hi:[1,0]
	v_pk_mul_f32 v[16:17], v[16:17], v[14:15] op_sel_hi:[1,0]
	v_mul_f32_e32 v213, v213, v14
